# ph8 epilogue: rstd per row computed once per thread and shared via LDS (1 ladder instead of 8 serial load+reduce ladders per lane), bit-identical
# speedup vs baseline: 1.0353x; 1.0153x over previous
.LBB0_984:
	s_lshl_b32 s60, s28, 8
	v_and_b32_e32 v134, 48, v180
	v_and_b32_e32 v135, 64, v180
	v_add_u32_e32 v134, v134, v178
	v_lshl_add_u32 v134, v135, 1, v134
	v_add_u32_e32 v132, s60, v134
	v_ashrrev_i32_e32 v133, 31, v132
	v_lshlrev_b64 v[128:129], 6, v[132:133]
	v_lshl_add_u64 v[136:137], s[16:17], 0, v[128:129]
	global_load_dwordx4 v[128:131], v[136:137], off
	global_load_dwordx4 v[142:145], v[136:137], off offset:16
	global_load_dwordx4 v[138:141], v[136:137], off offset:32
	global_load_dwordx4 v[146:149], v[136:137], off offset:48
	v_lshlrev_b32_e32 v135, 2, v134
	v_add_u32_e32 v135, 0x23000, v135
	s_waitcnt vmcnt(0)
	v_add_f32_e32 v128, v128, v129
	v_add_f32_e32 v130, v130, v131
	v_add_f32_e32 v142, v142, v143
	v_add_f32_e32 v144, v144, v145
	v_add_f32_e32 v138, v138, v139
	v_add_f32_e32 v140, v140, v141
	v_add_f32_e32 v146, v146, v147
	v_add_f32_e32 v148, v148, v149
	v_add_f32_e32 v128, v128, v130
	v_add_f32_e32 v142, v142, v144
	v_add_f32_e32 v138, v138, v140
	v_add_f32_e32 v146, v146, v148
	v_add_f32_e32 v128, v128, v142
	v_add_f32_e32 v138, v138, v146
	v_add_f32_e32 v128, v128, v138
	v_fmamk_f32 v128, v128, 0x3a800000, v214
	v_mul_f32_e32 v129, 0x4b800000, v128
	v_cmp_gt_f32_e32 vcc, s87, v128
	s_nop 1
	v_cndmask_b32_e32 v128, v128, v129, vcc
	v_rsq_f32_e32 v128, v128
	s_nop 0
	v_mul_f32_e32 v129, 0x45800000, v128
	v_cndmask_b32_e32 v128, v128, v129, vcc
	ds_write_b32 v135, v128
	v_lshlrev_b32_e32 v134, 2, v178
	v_add_u32_e32 v134, 0x23000, v134
	s_waitcnt lgkmcnt(0)
	s_barrier
	ds_read2_b32 v[150:151], v134 offset1:16
	ds_read2_b32 v[152:153], v134 offset0:32 offset1:48
	ds_read2_b32 v[154:155], v134 offset0:128 offset1:144
	ds_read2_b32 v[156:157], v134 offset0:160 offset1:176
	s_waitcnt lgkmcnt(0)
	v_pk_mul_f32 v[118:119], v[118:119], v[150:151] op_sel_hi:[1,0]
	v_pk_mul_f32 v[116:117], v[116:117], v[150:151] op_sel_hi:[1,0]
	v_pk_mul_f32 v[26:27], v[26:27], v[150:151] op_sel_hi:[1,0]
	v_pk_mul_f32 v[24:25], v[24:25], v[150:151] op_sel_hi:[1,0]
	v_pk_mul_f32 v[74:75], v[74:75], v[150:151] op_sel_hi:[1,0]
	v_pk_mul_f32 v[72:73], v[72:73], v[150:151] op_sel_hi:[1,0]
	v_pk_mul_f32 v[2:3], v[2:3], v[150:151] op_sel_hi:[1,0]
	v_pk_mul_f32 v[0:1], v[0:1], v[150:151] op_sel_hi:[1,0]
	v_pk_mul_f32 v[126:127], v[126:127], v[150:151] op_sel:[0,1] op_sel_hi:[1,1]
	v_pk_mul_f32 v[124:125], v[124:125], v[150:151] op_sel:[0,1] op_sel_hi:[1,1]
	v_pk_mul_f32 v[34:35], v[34:35], v[150:151] op_sel:[0,1] op_sel_hi:[1,1]
	v_pk_mul_f32 v[32:33], v[32:33], v[150:151] op_sel:[0,1] op_sel_hi:[1,1]
	v_pk_mul_f32 v[90:91], v[90:91], v[150:151] op_sel:[0,1] op_sel_hi:[1,1]
	v_pk_mul_f32 v[88:89], v[88:89], v[150:151] op_sel:[0,1] op_sel_hi:[1,1]
	v_pk_mul_f32 v[6:7], v[6:7], v[150:151] op_sel:[0,1] op_sel_hi:[1,1]
	v_pk_mul_f32 v[4:5], v[4:5], v[150:151] op_sel:[0,1] op_sel_hi:[1,1]
	v_pk_mul_f32 v[130:131], v[122:123], v[152:153] op_sel_hi:[1,0]
	v_pk_mul_f32 v[128:129], v[120:121], v[152:153] op_sel_hi:[1,0]
	v_pk_mul_f32 v[46:47], v[46:47], v[152:153] op_sel_hi:[1,0]
	v_pk_mul_f32 v[44:45], v[44:45], v[152:153] op_sel_hi:[1,0]
	v_pk_mul_f32 v[106:107], v[106:107], v[152:153] op_sel_hi:[1,0]
	v_pk_mul_f32 v[104:105], v[104:105], v[152:153] op_sel_hi:[1,0]
	v_pk_mul_f32 v[14:15], v[14:15], v[152:153] op_sel_hi:[1,0]
	v_pk_mul_f32 v[12:13], v[12:13], v[152:153] op_sel_hi:[1,0]
	v_pk_mul_f32 v[114:115], v[114:115], v[152:153] op_sel:[0,1] op_sel_hi:[1,1]
	v_pk_mul_f32 v[112:113], v[112:113], v[152:153] op_sel:[0,1] op_sel_hi:[1,1]
	v_pk_mul_f32 v[54:55], v[54:55], v[152:153] op_sel:[0,1] op_sel_hi:[1,1]
	v_pk_mul_f32 v[52:53], v[52:53], v[152:153] op_sel:[0,1] op_sel_hi:[1,1]
	v_pk_mul_f32 v[110:111], v[110:111], v[152:153] op_sel:[0,1] op_sel_hi:[1,1]
	v_pk_mul_f32 v[108:109], v[108:109], v[152:153] op_sel:[0,1] op_sel_hi:[1,1]
	v_pk_mul_f32 v[22:23], v[22:23], v[152:153] op_sel:[0,1] op_sel_hi:[1,1]
	v_pk_mul_f32 v[20:21], v[20:21], v[152:153] op_sel:[0,1] op_sel_hi:[1,1]
	v_pk_mul_f32 v[122:123], v[102:103], v[154:155] op_sel_hi:[1,0]
	v_pk_mul_f32 v[120:121], v[100:101], v[154:155] op_sel_hi:[1,0]
	v_pk_mul_f32 v[42:43], v[42:43], v[154:155] op_sel_hi:[1,0]
	v_pk_mul_f32 v[40:41], v[40:41], v[154:155] op_sel_hi:[1,0]
	v_pk_mul_f32 v[98:99], v[98:99], v[154:155] op_sel_hi:[1,0]
	v_pk_mul_f32 v[96:97], v[96:97], v[154:155] op_sel_hi:[1,0]
	v_pk_mul_f32 v[10:11], v[10:11], v[154:155] op_sel_hi:[1,0]
	v_pk_mul_f32 v[8:9], v[8:9], v[154:155] op_sel_hi:[1,0]
	v_pk_mul_f32 v[134:135], v[94:95], v[154:155] op_sel:[0,1] op_sel_hi:[1,1]
	v_pk_mul_f32 v[132:133], v[92:93], v[154:155] op_sel:[0,1] op_sel_hi:[1,1]
	v_pk_mul_f32 v[50:51], v[50:51], v[154:155] op_sel:[0,1] op_sel_hi:[1,1]
	v_pk_mul_f32 v[48:49], v[48:49], v[154:155] op_sel:[0,1] op_sel_hi:[1,1]
	v_pk_mul_f32 v[86:87], v[86:87], v[154:155] op_sel:[0,1] op_sel_hi:[1,1]
	v_pk_mul_f32 v[84:85], v[84:85], v[154:155] op_sel:[0,1] op_sel_hi:[1,1]
	v_pk_mul_f32 v[18:19], v[18:19], v[154:155] op_sel:[0,1] op_sel_hi:[1,1]
	v_pk_mul_f32 v[16:17], v[16:17], v[154:155] op_sel:[0,1] op_sel_hi:[1,1]
	v_pk_mul_f32 v[140:141], v[82:83], v[156:157] op_sel_hi:[1,0]
	v_pk_mul_f32 v[138:139], v[80:81], v[156:157] op_sel_hi:[1,0]
	v_pk_mul_f32 v[58:59], v[58:59], v[156:157] op_sel_hi:[1,0]
	v_pk_mul_f32 v[56:57], v[56:57], v[156:157] op_sel_hi:[1,0]
	v_pk_mul_f32 v[82:83], v[78:79], v[156:157] op_sel_hi:[1,0]
	v_pk_mul_f32 v[80:81], v[76:77], v[156:157] op_sel_hi:[1,0]
	v_pk_mul_f32 v[30:31], v[30:31], v[156:157] op_sel_hi:[1,0]
	v_pk_mul_f32 v[28:29], v[28:29], v[156:157] op_sel_hi:[1,0]
	v_pk_mul_f32 v[94:95], v[70:71], v[156:157] op_sel:[0,1] op_sel_hi:[1,1]
	v_pk_mul_f32 v[92:93], v[68:69], v[156:157] op_sel:[0,1] op_sel_hi:[1,1]
	v_pk_mul_f32 v[62:63], v[62:63], v[156:157] op_sel:[0,1] op_sel_hi:[1,1]
	v_pk_mul_f32 v[60:61], v[60:61], v[156:157] op_sel:[0,1] op_sel_hi:[1,1]
	v_pk_mul_f32 v[66:67], v[66:67], v[156:157] op_sel:[0,1] op_sel_hi:[1,1]
	v_pk_mul_f32 v[64:65], v[64:65], v[156:157] op_sel:[0,1] op_sel_hi:[1,1]
	v_pk_mul_f32 v[38:39], v[38:39], v[156:157] op_sel:[0,1] op_sel_hi:[1,1]
	v_pk_mul_f32 v[36:37], v[36:37], v[156:157] op_sel:[0,1] op_sel_hi:[1,1]
	v_cndmask_b32_e64 v68, 0, 1, s[22:23]
	v_cmp_ne_u32_e64 s[6:7], 1, v68
	s_and_saveexec_b64 s[62:63], s[0:1]
	s_cbranch_execz .LBB0_987
	s_and_b64 vcc, exec, s[6:7]
	ds_write_b128 v175, v[112:115]
	ds_write_b128 v175, v[52:55] offset:16
	ds_write_b128 v175, v[108:111] offset:512
	ds_write_b128 v175, v[20:23] offset:528
	ds_write_b128 v211, v[92:95]
	ds_write_b128 v175, v[60:63] offset:4112
	ds_write_b128 v175, v[64:67] offset:4608
	ds_write_b128 v175, v[36:39] offset:4624
	s_cbranch_vccnz .LBB0_987
	s_ashr_i32 s29, s28, 31
	v_lshl_add_u64 v[68:69], s[28:29], 1, v[176:177]
	v_mov_b64_e32 v[70:71], s[34:35]
	v_mad_u64_u32 v[70:71], s[14:15], v68, s77, v[70:71]
	s_lshl_b32 s14, s8, 8
	v_mad_i32_i24 v71, v69, s77, v71
	s_ashr_i32 s15, s14, 31
	v_lshl_add_u64 v[68:69], s[14:15], 2, v[70:71]
	v_lshlrev_b32_e32 v70, 2, v180
	v_mov_b32_e32 v71, v173
	v_lshl_add_u64 v[68:69], v[68:69], 0, v[70:71]
	global_store_dwordx4 v[68:69], v[92:95], off
	global_store_dwordx4 v[68:69], v[60:63], off offset:16
	global_store_dwordx4 v[68:69], v[64:67], off offset:512
	global_store_dwordx4 v[68:69], v[36:39], off offset:528
